# one static s_setprio 1 for waves 0-3 through stage A and the work-item phase (lever 4, other half)
# speedup vs baseline: 1.0132x; 1.0132x over previous
; __device__ __forceinline__ void chunkA_item(const Args& A, LAS unsigned char* lds, int tid, int lane, int wave, int ci, int ci_next, HeadConstA& H) {
;     ...
;     if (tid < 256) {
;         const int cp = tid >> 2, q = tid & 3;
;         f32x2_t xa[8], xb[8];
; #pragma unroll
;         for (int m = 0; m < 8; ++m) { xa[m] = (f32x2_t){0.f, 0.f}; xb[m] = (f32x2_t){0.f, 0.f}; }
;         const LAS float* Np = (const LAS float*)(lds + CA_N) + q * 16;
;         const LAS float* Ra = (const LAS float*)(lds + CA_RHS) + cp * 68; const LAS float* Rb = Ra + 64 * 68;
;         float a4[4], b4[4];
; #pragma unroll
;         for (int t = 0; t < 64; ++t) {
;             f32x2_t sa = {0.f, 0.f}, sb = {0.f, 0.f};
; #pragma unroll
;             for (int p = 0; p < ((t + 3) / 4 + 1) / 2; ++p) { const f32x2_t nv = *(const LAS f32x2_t*)(Np + t * 64 + 2 * p); sa += nv * xa[p]; sb += nv * xb[p]; }
;             float ua = sa.x + sa.y, ub = sb.x + sb.y;
;             ua += dppf<0xB1>(ua); ub += dppf<0xB1>(ub); ua += dppf<0x4E>(ua); ub += dppf<0x4E>(ub);
;             const float xta = Ra[t] - ua, xtb = Rb[t] - ub;
;             if (q == (t & 3)) { if ((t >> 2) & 1) { xa[t >> 3].y = xta; xb[t >> 3].y = xtb; } else { xa[t >> 3].x = xta; xb[t >> 3].x = xtb; } }
;             a4[t & 3] = xta; b4[t & 3] = xtb;
;             if ((t & 3) == 3 && q == 0) { *(LAS u32x2*)(lds + CA_XT + cp * 144 + (t - 3) * 2) = pack4(a4[0], a4[1], a4[2], a4[3]);
;                 *(LAS u32x2*)(lds + CA_XT + (64 + cp) * 144 + (t - 3) * 2) = pack4(b4[0], b4[1], b4[2], b4[3]); }
;         }
;     } else if (ci_next < 4096) {
;         const int cn = ci_next & 31, hn = (ci_next >> 5) & 7, bn = ci_next >> 8; const long rown = (long)bn * SEQ + cn * 64 - 1;
;         for (int l = tid - 256; l < 65 * 5; l += 256) { const int r = l / 5, sec = l % 5; long rr = rown + r; if (rr < 0) rr = 0;
;             const bf16_t* p = Z + rr * NZ + (sec == 0 ? hn * 64 : sec == 1 ? 512 + hn * 64 : sec == 2 ? 1024 + hn * 64 : sec == 3 ? 1536 : 1600);
;             unsigned dummy; asm volatile("global_load_dword %0, %1, off" : "=v"(dummy) : "v"(p) : "memory"); }
; __global__ void __launch_bounds__(512, 2) hymba_fwd(Args A) {
;     ...
;         { HeadConstA HC; HC.h = -1;
;           for (int it = blockIdx.x; it < N_CH; it += gridDim.x) chunkA_item(A, lds, tid, lane, wave, it, it + (int)gridDim.x, HC); }
.LBB0_147:
	v_readlane_b32 s98, v249, 3
	s_cmp_ge_u32 s98, 4
	s_cbranch_scc1 .Lprio_done
	s_setprio 1
